# MIXA loop: row-sum add chain moved out of the loop tail and issued per chunk after its mask (same order, separate accumulator registers)
# baseline (speedup 1.0000x reference)
; template <int DQK, bool MIXA, bool PIPE>
; DI void attn_item(const Params& P, int layer, char* smem, int b, int h, int qt) {
;     ...
;       for (int s2 = 0; s2 < 2; ++s2) { u32x4 t = {pkw[0][s2][0], pkw[0][s2][1], pkw[0][s2][2], pkw[0][s2][3]}; pf0[s2] = __builtin_bit_cast(bf16x8, t); }
; #pragma unroll
;       for (int j = 0; j < 4; ++j) {
;         const int s2 = j >> 1, d = j & 1;
;         o[d] = __builtin_amdgcn_mfma_f32_32x32x16_bf16(vf[d][0][s2], pf0[s2], o[d], 0, 0, 0);
;         chunk(1, 2 * j); chunk(1, 2 * j + 1);
;         __builtin_amdgcn_sched_barrier(0);
;       }
; #pragma unroll
;       for (int s2 = 0; s2 < 2; ++s2) { u32x4 t = {pkw[1][s2][0], pkw[1][s2][1], pkw[1][s2][2], pkw[1][s2][3]}; pf1[s2] = __builtin_bit_cast(bf16x8, t); }
; #pragma unroll
;       for (int j = 0; j < 4; ++j) {
;         const int s2 = j >> 1, d = j & 1;
;         o[d] = __builtin_amdgcn_mfma_f32_32x32x16_bf16(vf[d][1][s2], pf1[s2], o[d], 0, 0, 0);
;       }
;       l += ls2.x + ls2.y;
.LBB0_108:
	v_exp_f32_e32 v33, v33
	v_exp_f32_e32 v32, v32
	v_add_co_u32 v100, vcc, v100, v100
	v_cndmask_b32 v33, 0, v33, vcc
	s_nop 0
	v_add_co_u32 v100, vcc, v100, v100
	v_cndmask_b32 v32, 0, v32, vcc
	v_cvt_pk_bf16_f32 v36, v36, v37
	v_add_f32_e32 v42, v176, v34
	v_add_f32_e32 v43, v244, v35
	v_cvt_pk_bf16_f32 v35, v34, v35
	v_cvt_pk_bf16_f32 v37, v38, v39
	v_cvt_pk_bf16_f32 v38, v50, v51
	v_cvt_pk_bf16_f32 v39, v48, v49
	v_cvt_pk_bf16_f32 v40, v44, v45
	v_cvt_pk_bf16_f32 v41, v46, v47
	v_cvt_pk_bf16_f32 v34, v32, v33
	s_nop 1
	v_mfma_f32_32x32x16_bf16 v[0:15], v[80:83], v[34:37], v[0:15]
	v_add_f32_e64 v32, v42, v32
	v_add_f32_e64 v33, v43, v33
	v_add_f32_e32 v32, v32, v33
	v_add_f32_e32 v125, v125, v32
	v_mfma_f32_32x32x16_bf16 v[16:31], v[92:95], v[34:37], v[16:31]
	v_mfma_f32_32x32x16_bf16 v[0:15], v[84:87], v[38:41], v[0:15]
	v_mfma_f32_32x32x16_bf16 v[16:31], v[88:91], v[38:41], v[16:31]

; DI unsigned pk2(float a, float b) { f32x2 v = {a, b}; return __builtin_bit_cast(unsigned, __builtin_convertvector(v, bf16x2)); }
; template <int DQK, bool MIXA, bool PIPE>
; DI void attn_item(const Params& P, int layer, char* smem, int b, int h, int qt) {
;     ...
;       auto chunk = [&](int kb, int c) __attribute__((always_inline)) {
;         const int s2 = 1 - (c >> 2), e = 3 - (c & 3);
;         const int r0 = 8 * s2 + 2 * e;
;         if (MIXA && c == 4) mrot[kb] <<= 8;
;         f32x2 xv2 = {sacc[kb][r0], sacc[kb][r0 + 1]};
;         xv2 = xv2 * sl2v - mfixv;
;         if (MIXA) {
;           if (near) {
;             const int kl = 16 * (r0 >> 3) + 8 * H + (r0 & 7);
;             const int rel = kc * 64 + 32 * kb + kl - qpos;
;             xv2.x += biasT[rel + 192];
;             xv2.y += biasT[rel + 193];
;           }
;         }
;         f32x2 p2 = {__builtin_amdgcn_exp2f(xv2.x), __builtin_amdgcn_exp2f(xv2.y)};
;         if (MIXA) {
;           float px = p2.x, py = p2.y;
;           asm volatile("v_add_co_u32 %0, vcc, %0, %0\n\tv_cndmask_b32 %1, 0, %1, vcc" : "+v"(mrot[kb]), "+v"(py) : : "vcc");
;           asm volatile("v_add_co_u32 %0, vcc, %0, %0\n\tv_cndmask_b32 %1, 0, %1, vcc" : "+v"(mrot[kb]), "+v"(px) : : "vcc");
;           p2.x = px; p2.y = py;
;         }
;         ls2 += p2;
;         pkw[kb][s2][e] = pk2(p2.x, p2.y);
;       };
;       {
;         int c0 = 0;
; #pragma unroll
;         for (int s = 0; s < NS; ++s) {
;           sacc[1] = __builtin_amdgcn_mfma_f32_32x32x16_bf16(kf[1][s], qf[s], sacc[1], 0, 0, 0);
;           const int cend = (8 * (s + 1)) / NS;
; #pragma unroll
;           for (int c = 0; c < 8; ++c) if (c >= c0 && c < cend) chunk(0, c);
;           c0 = cend;
;           __builtin_amdgcn_sched_barrier(0);
;         }
;       }
;       bf16x8 pf0[2], pf1[2];
; #pragma unroll
;       for (int s2 = 0; s2 < 2; ++s2) { u32x4 t = {pkw[0][s2][0], pkw[0][s2][1], pkw[0][s2][2], pkw[0][s2][3]}; pf0[s2] = __builtin_bit_cast(bf16x8, t); }
; #pragma unroll
;       for (int j = 0; j < 4; ++j) {
;         const int s2 = j >> 1, d = j & 1;
;         o[d] = __builtin_amdgcn_mfma_f32_32x32x16_bf16(vf[d][0][s2], pf0[s2], o[d], 0, 0, 0);
;         chunk(1, 2 * j); chunk(1, 2 * j + 1);
;         __builtin_amdgcn_sched_barrier(0);
;       }
.Lmixa_back_0:
	v_exp_f32_e32 v62, v62
	v_lshrrev_b32_e32 v36, v147, v166
	v_exp_f32_e32 v63, v63
	v_lshlrev_b32_e32 v166, 8, v36
	v_add_co_u32 v166, vcc, v166, v166
	v_cndmask_b32 v63, 0, v63, vcc
	v_add_co_u32 v166, vcc, v166, v166
	v_cndmask_b32 v62, 0, v62, vcc
	v_add_f32_e32 v176, 0, v62
	v_add_f32_e32 v244, 0, v63
	s_cbranch_scc1 .Lmixa_near_1
.Lmixa_back_1:
	v_exp_f32_e32 v61, v61
	v_exp_f32_e32 v60, v60
	v_mfma_f32_32x32x16_bf16 v[32:47], v[32:35], v[76:79], v[228:243]
	v_add_co_u32 v166, vcc, v166, v166
	v_cndmask_b32 v61, 0, v61, vcc
	s_nop 0
	v_add_co_u32 v166, vcc, v166, v166
	v_cndmask_b32 v60, 0, v60, vcc
	v_add_f32_e32 v176, v176, v60
	v_add_f32_e32 v244, v244, v61
	s_cbranch_scc1 .Lmixa_near_2
.Lmixa_back_2:
	v_exp_f32_e32 v59, v59
	v_exp_f32_e32 v58, v58
	v_add_co_u32 v166, vcc, v166, v166
	v_cndmask_b32 v59, 0, v59, vcc
	v_add_co_u32 v166, vcc, v166, v166
	v_cndmask_b32 v58, 0, v58, vcc
	v_add_f32_e32 v176, v176, v58
	v_add_f32_e32 v244, v244, v59
	s_cbranch_scc1 .Lmixa_near_3
.Lmixa_back_3:
	v_mfma_f32_32x32x16_bf16 v[32:47], v[120:123], v[72:75], v[32:47]
	v_exp_f32_e32 v57, v57
	v_exp_f32_e32 v56, v56
	v_add_co_u32 v166, vcc, v166, v166
	v_cndmask_b32 v57, 0, v57, vcc
	s_nop 0
	v_add_co_u32 v166, vcc, v166, v166
	v_cndmask_b32 v56, 0, v56, vcc
	v_add_f32_e32 v176, v176, v56
	v_add_f32_e32 v244, v244, v57
	s_cbranch_scc1 .Lmixa_near_4
.Lmixa_back_4:
	v_exp_f32_e32 v55, v55
	v_lshlrev_b32_e32 v120, 8, v166
	v_exp_f32_e32 v54, v54
	v_add_co_u32 v120, vcc, v120, v120
	v_cndmask_b32 v55, 0, v55, vcc
	v_add_co_u32 v120, vcc, v120, v120
	v_cndmask_b32 v54, 0, v54, vcc
	v_add_f32_e32 v176, v176, v54
	v_add_f32_e32 v244, v244, v55
	s_cbranch_scc1 .Lmixa_near_5
.Lmixa_back_5:
	v_mfma_f32_32x32x16_bf16 v[32:47], v[116:119], v[68:71], v[32:47]
	v_exp_f32_e32 v53, v53
	v_exp_f32_e32 v52, v52
	v_add_co_u32 v120, vcc, v120, v120
	v_cndmask_b32 v53, 0, v53, vcc
	s_nop 0
	v_add_co_u32 v120, vcc, v120, v120
	v_cndmask_b32 v52, 0, v52, vcc
	v_add_f32_e32 v176, v176, v52
	v_add_f32_e32 v244, v244, v53
	s_cbranch_scc1 .Lmixa_near_6
.Lmixa_back_6:
	v_exp_f32_e32 v117, v51
	v_exp_f32_e32 v116, v50
	v_add_co_u32 v120, vcc, v120, v120
	v_cndmask_b32 v117, 0, v117, vcc
	v_add_co_u32 v120, vcc, v120, v120
	v_cndmask_b32 v116, 0, v116, vcc
	v_add_f32_e32 v176, v176, v116
	v_add_f32_e32 v244, v244, v117
	s_cbranch_scc1 .Lmixa_near_7
.Lmixa_back_7:
	v_mfma_f32_32x32x16_bf16 v[32:47], v[108:111], v[64:67], v[32:47]
	v_exp_f32_e32 v119, v49
	v_exp_f32_e32 v118, v48
	v_add_co_u32 v120, vcc, v120, v120
	v_cndmask_b32 v119, 0, v119, vcc
	v_cvt_pk_bf16_f32 v49, v116, v117
	v_cvt_pk_bf16_f32 v50, v52, v53
	v_cvt_pk_bf16_f32 v51, v54, v55
	v_add_co_u32 v120, vcc, v120, v120
	v_cndmask_b32 v118, 0, v118, vcc
	v_add_f32_e32 v176, v176, v118
	v_add_f32_e32 v244, v244, v119
	s_nop 0
	v_cvt_pk_bf16_f32 v48, v118, v119
	s_waitcnt lgkmcnt(0)
	s_nop 0
	v_mfma_f32_32x32x16_bf16 v[0:15], v[112:115], v[48:51], v[0:15]
	s_nop 1
	s_cbranch_scc1 .Lmixa_near_8
.Lmixa_back_8:
	v_lshrrev_b32_e32 v108, v147, v164
	v_exp_f32_e32 v47, v47
	v_lshlrev_b32_e32 v108, 8, v108
	v_exp_f32_e32 v46, v46
	v_add_co_u32 v108, vcc, v108, v108
	v_cndmask_b32 v47, 0, v47, vcc
	v_add_co_u32 v108, vcc, v108, v108
	v_cndmask_b32 v46, 0, v46, vcc
	v_add_f32_e32 v176, v176, v46
	v_add_f32_e32 v244, v244, v47
	s_cbranch_scc1 .Lmixa_near_9
.Lmixa_back_9:
	v_exp_f32_e32 v45, v45
	v_exp_f32_e32 v44, v44
	v_add_co_u32 v108, vcc, v108, v108
	v_cndmask_b32 v45, 0, v45, vcc
	s_nop 0
	v_add_co_u32 v108, vcc, v108, v108
	v_cndmask_b32 v44, 0, v44, vcc
	v_add_f32_e32 v176, v176, v44
	v_add_f32_e32 v244, v244, v45
	v_mfma_f32_32x32x16_bf16 v[16:31], v[104:107], v[48:51], v[16:31]
	s_cbranch_scc1 .Lmixa_near_10
.Lmixa_back_10:
	v_exp_f32_e32 v49, v43
	v_exp_f32_e32 v48, v42
	v_add_co_u32 v108, vcc, v108, v108
	v_cndmask_b32 v49, 0, v49, vcc
	v_add_co_u32 v108, vcc, v108, v108
	v_cndmask_b32 v48, 0, v48, vcc
	v_add_f32_e32 v176, v176, v48
	v_add_f32_e32 v244, v244, v49
	s_cbranch_scc1 .Lmixa_near_11
.Lmixa_back_11:
	v_exp_f32_e32 v51, v41
	v_exp_f32_e32 v50, v40
	v_cvt_pk_bf16_f32 v40, v56, v57
	v_cvt_pk_bf16_f32 v41, v58, v59
	v_cvt_pk_bf16_f32 v42, v60, v61
	v_cvt_pk_bf16_f32 v43, v62, v63
	v_add_co_u32 v108, vcc, v108, v108
	v_cndmask_b32 v51, 0, v51, vcc
	s_nop 0
	v_add_co_u32 v108, vcc, v108, v108
	v_cndmask_b32 v50, 0, v50, vcc
	v_add_f32_e32 v176, v176, v50
	v_add_f32_e32 v244, v244, v51
	s_nop 0
	v_mfma_f32_32x32x16_bf16 v[0:15], v[100:103], v[40:43], v[0:15]
	s_cbranch_scc1 .Lmixa_near_12
.Lmixa_back_12:
	v_exp_f32_e32 v39, v39
	v_lshlrev_b32_e32 v100, 8, v108
	v_exp_f32_e32 v38, v38
	v_add_co_u32 v100, vcc, v100, v100
	v_cndmask_b32 v39, 0, v39, vcc
	v_add_co_u32 v100, vcc, v100, v100
	v_cndmask_b32 v38, 0, v38, vcc
	v_add_f32_e32 v176, v176, v38
	v_add_f32_e32 v244, v244, v39
	s_cbranch_scc1 .Lmixa_near_13
.Lmixa_back_13:
	v_exp_f32_e32 v37, v37
	v_exp_f32_e32 v36, v36
	v_add_co_u32 v100, vcc, v100, v100
	v_cndmask_b32 v37, 0, v37, vcc
	s_nop 0
	v_add_co_u32 v100, vcc, v100, v100
	v_cndmask_b32 v36, 0, v36, vcc
	v_add_f32_e32 v176, v176, v36
	v_add_f32_e32 v244, v244, v37
	v_mfma_f32_32x32x16_bf16 v[16:31], v[96:99], v[40:43], v[16:31]
	s_cbranch_scc1 .Lmixa_near_14
